# one static s_setprio 1 for waves 0-3 for the duration of the attention units (reset to 0 after)
# baseline (speedup 1.0000x reference)
; __device__ __forceinline__ int fresh_tid() { int t = threadIdx.x; asm volatile("" : "+v"(t)); return t; }
; __global__ void __launch_bounds__(512, 2) fwd_kernel(Params p) {
;     ...
;             const float li = 0.8f - 0.6f * __expf(-0.3f * (float)l);
;             float lam;
;             { const int lane = fresh_tid() & 63;
;               const float s1 = wave_sum(p.lam_q1[l * 64 + lane] * p.lam_k1[l * 64 + lane]), s2 = wave_sum(p.lam_q2[l * 64 + lane] * p.lam_k2[l * 64 + lane]);
;               lam = expf(s1) - expf(s2) + li; }
;             att::Args A{Q1, Q2, K1c, K2c, VT, MIXA, p.subln_g + l * 128, lam, 1.f - li};
;             const int n_att = 512 + (l == 0 ? 64 : 0);
;             for (int u = cu; u < n_att; u += G) {
;                 if (u < 512) att::attn_unit(lds, A, u >> 6, (u >> 4) & 3, (u >> 6) * SEQ + (u & 15) * 128, 36);
.LBB0_669:
	v_writelane_b32 v255, s58, 38
	s_nop 1
	v_writelane_b32 v255, s59, 39
	s_or_b64 exec, exec, s[0:1]
	s_lshl_b32 s0, s72, 6
	s_waitcnt lgkmcnt(0)
	v_mov_b32_e32 v0, v192
	v_readlane_b32 s52, v252, 32
	s_barrier
	v_readlane_b32 s54, v252, 34
	v_and_or_b32 v160, v0, 63, s0
	v_readlane_b32 s55, v252, 35
	v_lshlrev_b64 v[0:1], 2, v[160:161]
	v_readlane_b32 s53, v252, 33
	v_readlane_b32 s56, v252, 36
	v_readlane_b32 s57, v252, 37
	v_readlane_b32 s58, v252, 38
	v_readlane_b32 s59, v252, 39
	s_mov_b64 s[50:51], s[54:55]
	v_readlane_b32 s60, v252, 40
	v_readlane_b32 s61, v252, 41
	v_readlane_b32 s62, v252, 42
	v_readlane_b32 s63, v252, 43
	s_mov_b64 s[52:53], s[56:57]
	v_lshl_add_u64 v[2:3], s[50:51], 0, v[0:1]
	s_mov_b64 s[54:55], s[58:59]
	s_mov_b64 s[56:57], s[60:61]
	global_load_dword v4, v[2:3], off
	v_lshl_add_u64 v[2:3], s[52:53], 0, v[0:1]
	global_load_dword v5, v[2:3], off
	v_lshl_add_u64 v[2:3], s[54:55], 0, v[0:1]
	v_lshl_add_u64 v[0:1], s[56:57], 0, v[0:1]
	global_load_dword v2, v[2:3], off
	v_xor_b32_e32 v6, 2, v197
	global_load_dword v0, v[0:1], off
	v_xor_b32_e32 v1, 1, v197
	v_cmp_lt_i32_e32 vcc, v1, v207
	v_readlane_b32 s0, v255, 26
	v_readlane_b32 s1, v255, 27
	v_cndmask_b32_e32 v1, v197, v1, vcc
	v_lshlrev_b32_e32 v209, 2, v1
	v_cmp_lt_i32_e32 vcc, v6, v207
	s_and_b64 s[0:1], s[0:1], exec
	s_movk_i32 s0, 0x240
	v_cndmask_b32_e32 v6, v197, v6, vcc
	v_lshlrev_b32_e32 v210, 2, v6
	s_cselect_b32 s10, s0, 0x200
	s_cmp_ge_i32 s2, s10
	v_readlane_b32 s64, v252, 44
	v_readlane_b32 s65, v252, 45
	v_readlane_b32 s66, v252, 46
	v_readlane_b32 s67, v252, 47
	s_mov_b64 s[58:59], s[62:63]
	s_waitcnt vmcnt(2)
	v_mul_f32_e32 v1, v4, v5
	ds_bpermute_b32 v1, v209, v1
	s_waitcnt vmcnt(0)
	v_mul_f32_e32 v3, v2, v0
	ds_bpermute_b32 v3, v209, v3
	s_waitcnt lgkmcnt(1)
	v_fmac_f32_e32 v1, v4, v5
	v_xor_b32_e32 v4, 4, v197
	v_cmp_lt_i32_e32 vcc, v4, v207
	s_waitcnt lgkmcnt(0)
	v_fmac_f32_e32 v3, v2, v0
	ds_bpermute_b32 v0, v210, v1
	ds_bpermute_b32 v2, v210, v3
	v_cndmask_b32_e32 v4, v197, v4, vcc
	v_lshlrev_b32_e32 v211, 2, v4
	v_xor_b32_e32 v4, 8, v197
	s_waitcnt lgkmcnt(1)
	v_add_f32_e32 v0, v1, v0
	s_waitcnt lgkmcnt(0)
	v_add_f32_e32 v1, v3, v2
	ds_bpermute_b32 v2, v211, v0
	ds_bpermute_b32 v3, v211, v1
	v_cmp_lt_i32_e32 vcc, v4, v207
	s_waitcnt lgkmcnt(1)
	v_add_f32_e32 v0, v0, v2
	v_cndmask_b32_e32 v4, v197, v4, vcc
	v_lshlrev_b32_e32 v212, 2, v4
	s_waitcnt lgkmcnt(0)
	v_add_f32_e32 v1, v1, v3
	ds_bpermute_b32 v2, v212, v0
	ds_bpermute_b32 v3, v212, v1
	v_xor_b32_e32 v4, 16, v197
	v_cmp_lt_i32_e32 vcc, v4, v207
	s_waitcnt lgkmcnt(1)
	v_add_f32_e32 v0, v0, v2
	v_cndmask_b32_e32 v4, v197, v4, vcc
	v_lshlrev_b32_e32 v213, 2, v4
	s_waitcnt lgkmcnt(0)
	v_add_f32_e32 v1, v1, v3
	ds_bpermute_b32 v2, v213, v0
	ds_bpermute_b32 v3, v213, v1
	v_cmp_lt_i32_e32 vcc, v204, v207
	s_waitcnt lgkmcnt(1)
	v_add_f32_e32 v2, v0, v2
	v_cndmask_b32_e32 v4, v197, v204, vcc
	v_lshlrev_b32_e32 v214, 2, v4
	s_waitcnt lgkmcnt(0)
	v_add_f32_e32 v0, v1, v3
	ds_bpermute_b32 v3, v214, v2
	ds_bpermute_b32 v1, v214, v0
	s_cbranch_scc1 .LBB0_708
	v_cvt_f32_u32_e32 v4, s72
	s_waitcnt lgkmcnt(1)
	v_add_f32_e32 v2, v2, v3
	v_readlane_b32 s52, v252, 32
	v_readlane_b32 s53, v252, 33
	v_mul_f32_e32 v3, 0xbe99999a, v4
	v_mul_f32_e32 v3, 0x3fb8aa3b, v3
	v_exp_f32_e32 v3, v3
	v_readlane_b32 s54, v252, 34
	v_readlane_b32 s55, v252, 35
	v_readlane_b32 s56, v252, 36
	v_readlane_b32 s57, v252, 37
	v_readlane_b32 s58, v252, 38
	v_readlane_b32 s59, v252, 39
	s_lshl_b32 s42, s72, 7
	v_readlane_b32 s60, v252, 40
	v_readlane_b32 s61, v252, 41
	v_readlane_b32 s62, v252, 42
	v_readlane_b32 s63, v252, 43
	s_mov_b64 s[52:53], s[56:57]
	s_lshl_b64 s[0:1], s[42:43], 2
	s_mov_b64 s[54:55], s[58:59]
	s_mov_b64 s[56:57], s[60:61]
	s_mov_b64 s[58:59], s[62:63]
	v_mul_f32_e32 v4, 0x3fb8aa3b, v2
	s_add_u32 s4, s58, s0
	s_mov_b32 s0, 0x3fb8aa3b
	v_mov_b32_e32 v6, 0x3f4ccccd
	v_fma_f32 v5, v2, s0, -v4
	v_fmamk_f32 v3, v3, 0xbf19999a, v6
	v_rndne_f32_e32 v6, v4
	v_fmac_f32_e32 v5, 0x32a5705f, v2
	v_sub_f32_e32 v4, v4, v6
	v_add_f32_e32 v4, v4, v5
	v_exp_f32_e32 v4, v4
	v_cvt_i32_f32_e32 v5, v6
	s_waitcnt lgkmcnt(0)
	v_add_f32_e32 v0, v0, v1
	s_addc_u32 s5, s59, s1
	s_mov_b32 s1, 0x42b17218
	v_ldexp_f32 v1, v4, v5
	v_mul_f32_e32 v4, 0x3fb8aa3b, v0
	v_fma_f32 v5, v0, s0, -v4
	v_rndne_f32_e32 v6, v4
	v_fmac_f32_e32 v5, 0x32a5705f, v0
	v_sub_f32_e32 v4, v4, v6
	v_add_f32_e32 v4, v4, v5
	v_exp_f32_e32 v4, v4
	v_cvt_i32_f32_e32 v5, v6
	s_mov_b32 s0, 0xc2ce8ed0
	v_cmp_ngt_f32_e32 vcc, s0, v2
	v_mov_b32_e32 v6, 0x7f800000
	v_sub_f32_e32 v215, 1.0, v3
	v_cndmask_b32_e32 v1, 0, v1, vcc
	v_cmp_nlt_f32_e32 vcc, s1, v2
	v_ldexp_f32 v2, v4, v5
	s_mov_b32 s11, s2
	v_cndmask_b32_e32 v1, v6, v1, vcc
	v_cmp_ngt_f32_e32 vcc, s0, v0
	v_readlane_b32 s64, v252, 44
	v_readlane_b32 s65, v252, 45
	v_cndmask_b32_e32 v2, 0, v2, vcc
	v_cmp_nlt_f32_e32 vcc, s1, v0
	v_readlane_b32 s66, v252, 46
	v_readlane_b32 s67, v252, 47
	v_cndmask_b32_e32 v0, v6, v2, vcc
	v_sub_f32_e32 v0, v1, v0
	v_add_f32_e32 v167, v3, v0
	v_mov_b32_e32 v168, v167
	v_mov_b32_e32 v169, v167
	v_readfirstlane_b32 s100, v192
	s_nop 3
	s_cmpk_lt_u32 s100, 0x100
	s_cbranch_scc0 .Lprio_done
	s_setprio 1
.Lprio_done:
	s_branch .LBB0_673

; __global__ void __launch_bounds__(512, 2) fwd_kernel(Params p) {
;     ...
;             for (int u = cu; u < n_att; u += G) {
;                 if (u < 512) att::attn_unit(lds, A, u >> 6, (u >> 4) & 3, (u >> 6) * SEQ + (u & 15) * 128, 36);
;                 else { const int v = u - 512; att::attn_unit(lds, A, v >> 3, (v >> 1) & 3, NLAT + (v >> 3) * CTXL + (v & 1) * 128, 4); }
;             }
.LBB0_708:
	s_setprio 0
	s_mov_b32 s8, 0
	s_mov_b64 s[0:1], -1
	s_waitcnt vmcnt(0)
	s_branch .LBB0_711
